# speedup vs baseline: 1.3549x; 1.0102x over previous
; #define LAS __attribute__((address_space(3)))
; __device__ __forceinline__ unsigned pk2(float lo, float hi) { return f2bf(lo) | (f2bf(hi) << 16); }
; template <int KIND, int MODE>
; __device__ __forceinline__ void scan_unit(Frame& F, int layer, int h, int vhalf, int grp) {
;     ...
;             for (int i = 0; i < 4; ++i) { const int c = tid + 512 * i, t = c >> 5, dc = (c & 31) * 8; const float wa = X[192 + t];
;                 const u32x4 k = pk[i]; u32x4 ko;
;                 if (MODE == 1) { const u32x4 q = qr[i]; u32x4 qo; qo.x = pk2(bflo(q.x) * 0.0625f, bfhi(q.x) * 0.0625f); qo.y = pk2(bflo(q.y) * 0.0625f, bfhi(q.y) * 0.0625f); qo.z = pk2(bflo(q.z) * 0.0625f, bfhi(q.z) * 0.0625f); qo.w = pk2(bflo(q.w) * 0.0625f, bfhi(q.w) * 0.0625f);
;                     *(LAS u32x4*)(QS + t * QST + dc) = qo; *(LAS u32x4*)(KS + t * QST + dc) = k; }
;                 ko.x = pk2(bflo(k.x) * wa, bfhi(k.x) * wa); ko.y = pk2(bflo(k.y) * wa, bfhi(k.y) * wa); ko.z = pk2(bflo(k.z) * wa, bfhi(k.z) * wa); ko.w = pk2(bflo(k.w) * wa, bfhi(k.w) * wa);
;                 *(LAS u32x4*)(K2 + t * QST + dc) = ko; }
.LBB0_532:
	s_waitcnt vmcnt(0) lgkmcnt(0)
	v_lshlrev_b32_e32 v101, 16, v97
	v_lshlrev_b32_e32 v100, 16, v96
	v_and_b32_e32 v97, 0xffff0000, v97
	v_and_b32_e32 v96, 0xffff0000, v96
	v_lshlrev_b32_e32 v103, 16, v99
	v_lshlrev_b32_e32 v102, 16, v98
	v_and_b32_e32 v99, 0xffff0000, v99
	v_and_b32_e32 v98, 0xffff0000, v98
	v_pk_mul_f32 v[96:97], v[96:97], s[64:65] op_sel_hi:[1,0]
	v_pk_mul_f32 v[98:99], v[98:99], s[64:65] op_sel_hi:[1,0]
	v_pk_mul_f32 v[100:101], v[100:101], s[64:65] op_sel_hi:[1,0]
	v_pk_mul_f32 v[102:103], v[102:103], s[64:65] op_sel_hi:[1,0]
	v_cvt_pk_bf16_f32 v96, v100, v96
	v_cvt_pk_bf16_f32 v97, v101, v97
	v_cvt_pk_bf16_f32 v98, v102, v98
	v_cvt_pk_bf16_f32 v99, v103, v99
	s_barrier
	ds_read_b32 v0, v148 offset:768
	ds_write_b128 v149, v[96:99]
	ds_write_b128 v149, v[92:95] offset:33792
	v_lshlrev_b32_e32 v97, 16, v93
	v_lshlrev_b32_e32 v96, 16, v92
	v_and_b32_e32 v93, 0xffff0000, v93
	v_and_b32_e32 v92, 0xffff0000, v92
	v_lshlrev_b32_e32 v99, 16, v95
	v_lshlrev_b32_e32 v98, 16, v94
	v_and_b32_e32 v95, 0xffff0000, v95
	v_and_b32_e32 v94, 0xffff0000, v94
	s_waitcnt lgkmcnt(2)
	v_pk_mul_f32 v[92:93], v[0:1], v[92:93] op_sel_hi:[0,1]
	v_pk_mul_f32 v[94:95], v[0:1], v[94:95] op_sel_hi:[0,1]
	v_pk_mul_f32 v[96:97], v[0:1], v[96:97] op_sel_hi:[0,1]
	v_pk_mul_f32 v[98:99], v[0:1], v[98:99] op_sel_hi:[0,1]
	v_cvt_pk_bf16_f32 v92, v96, v92
	v_cvt_pk_bf16_f32 v93, v97, v93
	v_cvt_pk_bf16_f32 v94, v98, v94
	v_cvt_pk_bf16_f32 v95, v99, v95
	ds_write_b128 v170, v[92:95]
	v_lshlrev_b32_e32 v93, 16, v89
	v_lshlrev_b32_e32 v92, 16, v88
	v_and_b32_e32 v89, 0xffff0000, v89
	v_and_b32_e32 v88, 0xffff0000, v88
	v_lshlrev_b32_e32 v95, 16, v91
	v_lshlrev_b32_e32 v94, 16, v90
	v_and_b32_e32 v91, 0xffff0000, v91
	v_and_b32_e32 v90, 0xffff0000, v90
	v_pk_mul_f32 v[88:89], v[88:89], s[64:65] op_sel_hi:[1,0]
	v_pk_mul_f32 v[90:91], v[90:91], s[64:65] op_sel_hi:[1,0]
	v_pk_mul_f32 v[92:93], v[92:93], s[64:65] op_sel_hi:[1,0]
	v_pk_mul_f32 v[94:95], v[94:95], s[64:65] op_sel_hi:[1,0]
	v_cvt_pk_bf16_f32 v88, v92, v88
	v_cvt_pk_bf16_f32 v89, v93, v89
	v_cvt_pk_bf16_f32 v90, v94, v90
	v_cvt_pk_bf16_f32 v91, v95, v91
	ds_read_b32 v0, v171 offset:768
	ds_write_b128 v172, v[88:91]
	ds_write_b128 v172, v[84:87] offset:33792
	v_lshlrev_b32_e32 v89, 16, v85
	v_lshlrev_b32_e32 v88, 16, v84
	v_and_b32_e32 v85, 0xffff0000, v85
	v_and_b32_e32 v84, 0xffff0000, v84
	v_lshlrev_b32_e32 v91, 16, v87
	v_lshlrev_b32_e32 v90, 16, v86
	v_and_b32_e32 v87, 0xffff0000, v87
	v_and_b32_e32 v86, 0xffff0000, v86
	s_waitcnt lgkmcnt(2)
	v_pk_mul_f32 v[84:85], v[0:1], v[84:85] op_sel_hi:[0,1]
	v_pk_mul_f32 v[86:87], v[0:1], v[86:87] op_sel_hi:[0,1]
	v_pk_mul_f32 v[88:89], v[0:1], v[88:89] op_sel_hi:[0,1]
	v_pk_mul_f32 v[90:91], v[0:1], v[90:91] op_sel_hi:[0,1]
	v_cvt_pk_bf16_f32 v84, v88, v84
	v_cvt_pk_bf16_f32 v85, v89, v85
	v_cvt_pk_bf16_f32 v86, v90, v86
	v_cvt_pk_bf16_f32 v87, v91, v87
	ds_write_b128 v173, v[84:87]
	v_lshlrev_b32_e32 v85, 16, v81
	v_lshlrev_b32_e32 v84, 16, v80
	v_and_b32_e32 v81, 0xffff0000, v81
	v_and_b32_e32 v80, 0xffff0000, v80
	v_lshlrev_b32_e32 v87, 16, v83
	v_lshlrev_b32_e32 v86, 16, v82
	v_and_b32_e32 v83, 0xffff0000, v83
	v_and_b32_e32 v82, 0xffff0000, v82
	v_pk_mul_f32 v[80:81], v[80:81], s[64:65] op_sel_hi:[1,0]
	v_pk_mul_f32 v[82:83], v[82:83], s[64:65] op_sel_hi:[1,0]
	v_pk_mul_f32 v[84:85], v[84:85], s[64:65] op_sel_hi:[1,0]
	v_pk_mul_f32 v[86:87], v[86:87], s[64:65] op_sel_hi:[1,0]
	v_cvt_pk_bf16_f32 v80, v84, v80
	v_cvt_pk_bf16_f32 v81, v85, v81
	v_cvt_pk_bf16_f32 v82, v86, v82
	v_cvt_pk_bf16_f32 v83, v87, v83
	ds_read_b32 v0, v174 offset:768
	ds_write_b128 v175, v[80:83]
	ds_write_b128 v175, v[76:79] offset:33792
	v_lshlrev_b32_e32 v81, 16, v77
	v_lshlrev_b32_e32 v80, 16, v76
	v_and_b32_e32 v77, 0xffff0000, v77
	v_and_b32_e32 v76, 0xffff0000, v76
	v_lshlrev_b32_e32 v83, 16, v79
	v_lshlrev_b32_e32 v82, 16, v78
	v_and_b32_e32 v79, 0xffff0000, v79
	v_and_b32_e32 v78, 0xffff0000, v78
	s_waitcnt lgkmcnt(2)
	v_pk_mul_f32 v[76:77], v[0:1], v[76:77] op_sel_hi:[0,1]
	v_pk_mul_f32 v[78:79], v[0:1], v[78:79] op_sel_hi:[0,1]
	v_pk_mul_f32 v[80:81], v[0:1], v[80:81] op_sel_hi:[0,1]
	v_pk_mul_f32 v[82:83], v[0:1], v[82:83] op_sel_hi:[0,1]
	v_cvt_pk_bf16_f32 v76, v80, v76
	v_cvt_pk_bf16_f32 v77, v81, v77
	v_cvt_pk_bf16_f32 v78, v82, v78
	v_cvt_pk_bf16_f32 v79, v83, v79
	ds_write_b128 v176, v[76:79]
	v_lshlrev_b32_e32 v77, 16, v73
	v_lshlrev_b32_e32 v76, 16, v72
	v_and_b32_e32 v73, 0xffff0000, v73
	v_and_b32_e32 v72, 0xffff0000, v72
	v_lshlrev_b32_e32 v79, 16, v75
	v_lshlrev_b32_e32 v78, 16, v74
	v_and_b32_e32 v75, 0xffff0000, v75
	v_and_b32_e32 v74, 0xffff0000, v74
	v_pk_mul_f32 v[72:73], v[72:73], s[64:65] op_sel_hi:[1,0]
	v_pk_mul_f32 v[74:75], v[74:75], s[64:65] op_sel_hi:[1,0]
	v_pk_mul_f32 v[76:77], v[76:77], s[64:65] op_sel_hi:[1,0]
	v_pk_mul_f32 v[78:79], v[78:79], s[64:65] op_sel_hi:[1,0]
	v_cvt_pk_bf16_f32 v72, v76, v72
	v_cvt_pk_bf16_f32 v73, v77, v73
	v_cvt_pk_bf16_f32 v74, v78, v74
	v_cvt_pk_bf16_f32 v75, v79, v75
	ds_read_b32 v0, v177 offset:768
	ds_write_b128 v178, v[72:75]
	ds_write_b128 v178, v[68:71] offset:33792
	v_lshlrev_b32_e32 v73, 16, v69
	v_lshlrev_b32_e32 v72, 16, v68
	v_and_b32_e32 v69, 0xffff0000, v69
	v_and_b32_e32 v68, 0xffff0000, v68
	v_lshlrev_b32_e32 v75, 16, v71
	v_lshlrev_b32_e32 v74, 16, v70
	v_and_b32_e32 v71, 0xffff0000, v71
	v_and_b32_e32 v70, 0xffff0000, v70
	s_waitcnt lgkmcnt(2)
	v_pk_mul_f32 v[68:69], v[0:1], v[68:69] op_sel_hi:[0,1]
	v_pk_mul_f32 v[70:71], v[0:1], v[70:71] op_sel_hi:[0,1]
	v_pk_mul_f32 v[72:73], v[0:1], v[72:73] op_sel_hi:[0,1]
	v_pk_mul_f32 v[74:75], v[0:1], v[74:75] op_sel_hi:[0,1]
	v_cvt_pk_bf16_f32 v68, v72, v68
	v_cvt_pk_bf16_f32 v69, v73, v69
	v_cvt_pk_bf16_f32 v70, v74, v70
	v_cvt_pk_bf16_f32 v71, v75, v71
	ds_write_b128 v179, v[68:71]
	s_waitcnt lgkmcnt(0)
	s_barrier
; #define LAS __attribute__((address_space(3)))
; __device__ __forceinline__ unsigned pk2(float lo, float hi) { return f2bf(lo) | (f2bf(hi) << 16); }
; #define MFMA16(a, b, c) __builtin_amdgcn_mfma_f32_16x16x32_bf16((a), (b), (c), 0, 0, 0)
; template <int KIND, int MODE>
; __device__ __forceinline__ void scan_unit(Frame& F, int layer, int h, int vhalf, int grp) {
;     ...
;             for (int tt = 0; tt < 2; ++tt) { const int ttile = 2 * (w & 1) + tt; f32x4 acc = (f32x4){0.f, 0.f, 0.f, 0.f};
; #pragma unroll
;                 for (int sl = 0; sl < NSL; ++sl) { const bf16x8 a = *(const LAS bf16x8*)(KS + (16 * stile + li) * QST + 32 * sl + 8 * g), bb = *(const LAS bf16x8*)(QS + (16 * ttile + li) * QST + 32 * sl + 8 * g); acc = MFMA16(a, bb, acc); }
;                 const int t = 16 * ttile + li; float p[4]; float rs = 0.f;
;                 float mt = 0.f; f32x4 cs = (f32x4){0.f, 0.f, 0.f, 0.f};
;                 if (KIND) { mt = X[64 + t]; cs = *(const LAS f32x4*)(X + 16 * stile + 4 * g); }
; #pragma unroll
;                 for (int r = 0; r < 4; ++r) { const int s = 16 * stile + 4 * g + r; float v = acc[r]; if (KIND) v *= __expf(fminf(cs[r] - mt, 0.f)); p[r] = (s <= t) ? v : 0.f; rs += p[r]; }
;                 u32x2 pw; pw.x = pk2(p[0], p[1]); pw.y = pk2(p[2], p[3]); *(LAS u32x2*)(PS + t * PST + 16 * stile + 4 * g) = pw;
;                 if (KIND) { rs += __shfl_xor(rs, 16); rs += __shfl_xor(rs, 32); if (g == 0) X[640 + stile * 64 + t] = rs; }
	ds_read_b128 v[68:71], v120 offset:33792
	ds_read_b128 v[72:75], v205
	ds_read_b128 v[76:79], v120 offset:33856
	ds_read_b128 v[80:83], v205 offset:64
	s_waitcnt lgkmcnt(2)
	v_mfma_f32_16x16x32_bf16 v[68:71], v[68:71], v[72:75], 0
	ds_read_b128 v[72:75], v120 offset:33920
	ds_read_b128 v[84:87], v205 offset:128
	s_waitcnt lgkmcnt(2)
	v_mfma_f32_16x16x32_bf16 v[68:71], v[76:79], v[80:83], v[68:71]
	ds_read_b128 v[76:79], v120 offset:33984
	ds_read_b128 v[80:83], v205 offset:192
	s_waitcnt lgkmcnt(2)
	v_mfma_f32_16x16x32_bf16 v[68:71], v[72:75], v[84:87], v[68:71]
	ds_read_b128 v[72:75], v120 offset:34048
	ds_read_b128 v[84:87], v205 offset:256
	s_waitcnt lgkmcnt(2)
	v_mfma_f32_16x16x32_bf16 v[68:71], v[76:79], v[80:83], v[68:71]
	ds_read_b128 v[76:79], v120 offset:34112
	ds_read_b128 v[80:83], v205 offset:320
	s_waitcnt lgkmcnt(2)
	v_mfma_f32_16x16x32_bf16 v[68:71], v[72:75], v[84:87], v[68:71]
	ds_read_b128 v[72:75], v120 offset:34176
	ds_read_b128 v[84:87], v205 offset:384
	s_waitcnt lgkmcnt(2)
	v_mfma_f32_16x16x32_bf16 v[68:71], v[76:79], v[80:83], v[68:71]
	ds_read_b128 v[76:79], v120 offset:34240
	ds_read_b128 v[80:83], v205 offset:448
	s_waitcnt lgkmcnt(2)
	v_mfma_f32_16x16x32_bf16 v[68:71], v[72:75], v[84:87], v[68:71]
	ds_read_b32 v0, v180 offset:256
	ds_read_b128 v[72:75], v121
	s_waitcnt lgkmcnt(0)
	v_sub_f32_e32 v73, v73, v0
	v_min_f32_e32 v73, 0, v73
	v_mul_f32_e32 v73, 0x3fb8aa3b, v73
	v_mfma_f32_16x16x32_bf16 v[68:71], v[76:79], v[80:83], v[68:71]
	v_sub_f32_e32 v72, v72, v0
	v_exp_f32_e32 v76, v73
	v_sub_f32_e32 v73, v74, v0
	v_min_f32_e32 v72, 0, v72
	v_min_f32_e32 v73, 0, v73
	v_mul_f32_e32 v72, 0x3fb8aa3b, v72
	v_sub_f32_e32 v0, v75, v0
	v_mul_f32_e32 v73, 0x3fb8aa3b, v73
	v_exp_f32_e32 v72, v72
	v_min_f32_e32 v0, 0, v0
	v_exp_f32_e32 v73, v73
	v_mul_f32_e32 v0, 0x3fb8aa3b, v0
	v_exp_f32_e32 v0, v0
	v_mul_f32_e32 v74, v69, v76
	v_mov_b32_e32 v69, v70
	v_pk_mul_f32 v[68:69], v[68:69], v[72:73]
	v_mul_f32_e32 v0, v71, v0
	v_cndmask_b32_e64 v68, v68, 0, s[24:25]
	v_add_f32_e32 v70, 0, v68
	v_cndmask_b32_e64 v71, 0, v74, s[28:29]
	v_cndmask_b32_e64 v69, v69, 0, s[26:27]
	v_add_f32_e32 v70, v71, v70
	v_cndmask_b32_e64 v0, v0, 0, s[30:31]
	v_add_f32_e32 v70, v69, v70
	v_add_f32_e32 v70, v0, v70
	v_and_b32_sdwa v72, v69, v224 dst_sel:DWORD dst_unused:UNUSED_PAD src0_sel:WORD_1 src1_sel:DWORD
	v_add3_u32 v69, v69, v72, s81
	ds_bpermute_b32 v72, v128, v70
	v_and_b32_sdwa v73, v68, v224 dst_sel:DWORD dst_unused:UNUSED_PAD src0_sel:WORD_1 src1_sel:DWORD
	v_add3_u32 v73, v68, v73, s81
	v_and_b32_sdwa v68, v0, v224 dst_sel:DWORD dst_unused:UNUSED_PAD src0_sel:WORD_1 src1_sel:DWORD
	v_and_b32_sdwa v74, v71, v224 dst_sel:DWORD dst_unused:UNUSED_PAD src0_sel:WORD_1 src1_sel:DWORD
	v_add3_u32 v0, v0, v68, s81
	v_add3_u32 v71, v71, v74, s81
	v_and_b32_e32 v74, 0xffff0000, v0
	s_waitcnt lgkmcnt(0)
	v_add_f32_e32 v0, v70, v72
	ds_bpermute_b32 v68, v129, v0
	v_and_b32_e32 v70, 0xffff0000, v71
	v_or_b32_sdwa v71, v74, v69 dst_sel:DWORD dst_unused:UNUSED_PAD src0_sel:DWORD src1_sel:WORD_1
	v_or_b32_sdwa v70, v70, v73 dst_sel:DWORD dst_unused:UNUSED_PAD src0_sel:DWORD src1_sel:WORD_1
	ds_write_b64 v206, v[70:71]
	s_and_saveexec_b64 s[0:1], s[12:13]
	s_cbranch_execz .LBB0_534
	s_waitcnt lgkmcnt(1)
	v_add_f32_e32 v0, v0, v68
	ds_write_b32 v181, v0 offset:2560
